# GEMM K-loops: fragment ds_reads software-pipelined one k-substep ahead (phase 2); XCD-aware tile-to-block mapping in phases 2 and 7 for L2 reuse
# speedup vs baseline: 1.0215x; 1.0070x over previous
; DI void phase2(const Params& P, unsigned char* lds) {
;   GemmDesc g{(const bf16_t*)(P.ws + OFF_H), 1024, (const bf16_t*)(P.ws + OFF_WIN_T), 1024, 1024};
;   EpiP1 e{(bf16_t*)(P.ws + OFF_USH), (bf16_t*)(P.ws + OFF_UMLA), (bf16_t*)((unsigned char*)P.out + OOFF_G)};
;   for (int t = blockIdx.x; t < 66 * 14; t += gridDim.x) gemm_tile(g, (t / 14) * BM, (t % 14) * BN, lds, e);
.LBB0_187:
	s_cmp_lt_i32 s96, 3
	s_waitcnt lgkmcnt(0)
	s_cselect_b64 s[0:1], -1, 0
	s_cmp_gt_i32 s97, 2
	s_cselect_b64 s[2:3], -1, 0
	s_and_b64 s[0:1], s[0:1], s[2:3]
	s_andn2_b64 vcc, exec, s[0:1]
	v_writelane_b32 v243, s78, 34
	s_nop 1
	v_writelane_b32 v243, s79, 35
	s_cbranch_vccnz .LBB0_604
	v_writelane_b32 v243, s88, 36
	s_cmpk_gt_i32 s76, 0x39b
	v_writelane_b32 v243, s76, 37
	s_cbranch_scc1 .LBB0_550
	s_add_u32 s52, s94, 0x5a68000
	s_addc_u32 s53, s95, 0
	s_add_u32 s54, s94, 0x10000
	s_addc_u32 s55, s95, 0
	s_add_u32 s56, s94, 0xb00000
	s_addc_u32 s57, s95, 0
	s_add_u32 s62, s94, 0x44c0000
	s_addc_u32 s63, s95, 0
	v_readlane_b32 s0, v243, 34
	v_readlane_b32 s1, v243, 35
	s_add_u32 s64, s0, 0xd8
	s_movk_i32 s72, 0xf200
	s_movk_i32 s80, 0xf240
	s_addc_u32 s65, s1, 0
	v_mov_b32_e32 v161, 0
	s_movk_i32 s2, 0x90
	s_mov_b32 s3, 0x20000
	s_mov_b32 s89, 0x40000
	s_mov_b32 s90, 0x60000
	s_mov_b64 s[66:67], 0x100
	s_load_dword s91, s[64:65], 0x0
	s_movk_i32 s88, 0x39c
	s_movk_i32 s68, 0x3ffe
	s_movk_i32 s69, 0x3ffd
	s_movk_i32 s74, 0x3ff8
	s_movk_i32 s75, 0x3ff7
	s_movk_i32 s33, 0x3ff6
	s_movk_i32 s44, 0x3ff5
	s_movk_i32 s45, 0x3ff0
	s_movk_i32 s46, 0x3fef
	s_movk_i32 s47, 0x3fee
	s_movk_i32 s48, 0x3fed
	s_movk_i32 s49, 0x3fe8
	s_movk_i32 s50, 0x3fe7
	s_movk_i32 s51, 0x3fe6
	s_movk_i32 s58, 0x3fe5
	s_movk_i32 s59, 0x6ff
	s_movk_i32 s70, 0xb9f
	s_mov_b32 s73, -1
	s_movk_i32 s71, 0x6df
	s_mov_b32 s81, -1
	v_readlane_b32 s0, v243, 37
	s_waitcnt lgkmcnt(0)
	s_cmpk_eq_u32 s91, 0x100
	s_cbranch_scc0 .Lg2_lim_done
	s_movk_i32 s88, 0x400
.Lg2_lim_done:
	s_branch .LBB0_191
.LBB0_190:
	s_or_b64 exec, exec, s[4:5]
	s_add_i32 s0, s91, s0
	s_cmp_lt_i32 s0, s88
	s_cbranch_scc0 .LBB0_550
.LBB0_191:
	s_cmpk_eq_u32 s91, 0x100
	s_cbranch_scc1 .Lg2_swz
	s_mul_hi_i32 s1, s0, 0x92492493
	s_add_i32 s1, s1, s0
	s_lshr_b32 s4, s1, 31
	s_ashr_i32 s1, s1, 3
	s_add_i32 s1, s1, s4
	s_mul_i32 s7, s1, 14
	s_sub_i32 s7, s0, s7
	s_branch .Lg2_swz_done
.Lg2_swz:
	s_and_b32 s4, s0, 0xff
	s_lshr_b32 s5, s0, 8
	s_and_b32 s6, s4, 7
	s_lshr_b32 s4, s4, 3
	s_lshl_b32 s5, s5, 3
	s_add_u32 s5, s5, s6
	s_lshl_b32 s5, s5, 5
	s_add_u32 s5, s5, s4
	s_cmpk_ge_u32 s5, 0x39c
	s_cbranch_scc1 .LBB0_550
	s_cmpk_ge_u32 s5, 0x1ce
	s_cselect_b32 s6, 7, 0
	s_cselect_b32 s7, 0x1ce, 0
	s_sub_u32 s5, s5, s7
	s_mul_i32 s1, s5, 0x2493
	s_lshr_b32 s1, s1, 16
	s_mul_i32 s4, s1, 7
	s_sub_u32 s4, s5, s4
	s_add_u32 s7, s4, s6
; #define GLOAD(kt) do { const int ko = (kt) * BK; \
;     ra0 = *(const uint4*)(gA + ko); ra1 = *(const uint4*)(gA + sA + ko); ra2 = *(const uint4*)(gA + 2 * sA + ko); ra3 = *(const uint4*)(gA + 3 * sA + ko); \
;     rb0 = *(const uint4*)(gB + ko); rb1 = *(const uint4*)(gB + sB + ko); rb2 = *(const uint4*)(gB + 2 * sB + ko); rb3 = *(const uint4*)(gB + 3 * sB + ko); } while (0)
; #define LSTORE(st) do { \
;     *(uint4*)(lA + (st) * ASZ) = ra0; *(uint4*)(lA + (st) * ASZ + 64 * LDT) = ra1; *(uint4*)(lA + (st) * ASZ + 128 * LDT) = ra2; *(uint4*)(lA + (st) * ASZ + 192 * LDT) = ra3; \
;     *(uint4*)(lB + (st) * BSZ) = rb0; *(uint4*)(lB + (st) * BSZ + 64 * LDT) = rb1; *(uint4*)(lB + (st) * BSZ + 128 * LDT) = rb2; *(uint4*)(lB + (st) * BSZ + 192 * LDT) = rb3; } while (0)
; template <class Epi>
; DI void gemm_tile(const GemmDesc g, int m0, int n0, unsigned char* lds, Epi& epi) {
;     ...
;       for (int e = 0; e < 16; ++e) acc[i][j][e] = 0.f;
;   uint4 ra0, ra1, ra2, ra3, rb0, rb1, rb2, rb3;
;   const int nk = g.K / BK;
;   const bf16_t* gA = g.A + (size_t)(m0 + (tid >> 3)) * g.lda + (tid & 7) * 8;
;   const bf16_t* gB = g.Bt + (size_t)(n0 + (tid >> 3)) * g.ldb + (tid & 7) * 8;
;   const size_t sA = (size_t)64 * g.lda, sB = (size_t)64 * g.ldb;
;   bf16_t* lA = As + (tid >> 3) * LDT + (tid & 7) * 8;
;   bf16_t* lB = Bs + (tid >> 3) * LDT + (tid & 7) * 8;
;   const bf16_t* fA = As + (wm * 128 + (lane & 31)) * LDT + (lane >> 5) * 8;
;   const bf16_t* fB = Bs + (wn * 64 + (lane & 31)) * LDT + (lane >> 5) * 8;
;     ...
;   __syncthreads();
;   GLOAD(0);
;   LSTORE(0);
;   __syncthreads();
.Lg2_swz_done:
	v_mov_b32_e32 v174, v208
	s_lshl_b32 s8, s1, 8
	v_ashrrev_i32_e32 v43, 3, v174
	v_add_u32_e32 v0, s8, v43
	v_ashrrev_i32_e32 v1, 31, v0
	v_lshlrev_b64 v[38:39], 11, v[0:1]
	v_lshlrev_b32_e32 v2, 4, v174
	v_lshl_add_u64 v[0:1], s[52:53], 0, v[38:39]
	v_and_b32_e32 v160, 0x70, v2
	s_mov_b32 s1, s7
	v_lshl_add_u64 v[0:1], v[0:1], 0, v[160:161]
	s_lshl_b32 s1, s1, 8
	v_add_co_u32_e32 v4, vcc, s3, v0
	v_add_u32_e32 v2, s1, v43
	s_nop 0
	v_addc_co_u32_e32 v5, vcc, 0, v1, vcc
	v_ashrrev_i32_e32 v3, 31, v2
	v_add_co_u32_e32 v10, vcc, s89, v0
	v_lshlrev_b64 v[40:41], 11, v[2:3]
	s_nop 0
	v_addc_co_u32_e32 v11, vcc, 0, v1, vcc
	v_lshl_add_u64 v[2:3], s[54:55], 0, v[40:41]
	s_barrier
	global_load_dwordx4 v[6:9], v[4:5], off
	s_nop 0
	global_load_dwordx4 v[10:13], v[10:11], off
	v_add_co_u32_e32 v4, vcc, s90, v0
	v_lshl_add_u64 v[2:3], v[2:3], 0, v[160:161]
	s_nop 0
	v_addc_co_u32_e32 v5, vcc, 0, v1, vcc
	global_load_dwordx4 v[14:17], v[0:1], off
	global_load_dwordx4 v[18:21], v[2:3], off
	v_add_co_u32_e32 v0, vcc, s3, v2
	v_and_b32_e32 v175, 31, v174
	s_nop 0
	v_addc_co_u32_e32 v1, vcc, 0, v3, vcc
	global_load_dwordx4 v[22:25], v[4:5], off
	global_load_dwordx4 v[26:29], v[0:1], off
	v_add_co_u32_e32 v0, vcc, s89, v2
	v_ashrrev_i32_e32 v5, 1, v174
	s_nop 0
	v_addc_co_u32_e32 v1, vcc, 0, v3, vcc
	v_add_co_u32_e32 v2, vcc, s90, v2
	v_bfe_u32 v176, v174, 5, 1
	s_nop 0
	v_addc_co_u32_e32 v3, vcc, 0, v3, vcc
	global_load_dwordx4 v[30:33], v[0:1], off
	global_load_dwordx4 v[34:37], v[2:3], off
	v_and_b32_e32 v44, 0xdf, v174
	v_and_b32_e32 v177, 0xffffff80, v5
	s_mov_b32 s6, 0x12000
	v_and_b32_e32 v45, 7, v174
	v_lshlrev_b32_e32 v42, 4, v176
	v_mul_u32_u24_e32 v5, 0x90, v44
	v_mad_u64_u32 v[162:163], s[4:5], v43, s2, v[160:161]
	v_or_b32_e32 v43, v177, v175
	s_mov_b32 s9, 0
	v_mov_b32_e32 v0, v161
	v_mov_b32_e32 v1, v161
	v_mov_b32_e32 v2, v161
	v_mov_b32_e32 v3, v161
	v_mov_b32_e32 v4, v161
	v_add3_u32 v163, v5, v42, s6
	v_add_u32_e32 v178, 0x12000, v162
	v_mad_u64_u32 v[164:165], s[4:5], v43, s2, v[42:43]
	v_lshl_add_u64 v[166:167], s[94:95], 0, v[38:39]
	v_lshl_add_u64 v[168:169], s[94:95], 0, v[40:41]
	v_lshlrev_b32_e32 v160, 4, v45
	v_mov_b32_e32 v5, v161
	v_mov_b32_e32 v38, v161
	v_mov_b32_e32 v39, v161
	v_mov_b32_e32 v40, v161
	v_mov_b32_e32 v41, v161
	v_mov_b32_e32 v42, v161
	v_mov_b32_e32 v43, v161
	v_mov_b32_e32 v44, v161
	v_mov_b32_e32 v45, v161
	v_mov_b32_e32 v46, v161
	v_mov_b32_e32 v47, v161
	v_mov_b32_e32 v48, v161
	v_mov_b32_e32 v49, v161
	v_mov_b32_e32 v50, v161
	v_mov_b32_e32 v51, v161
	v_mov_b32_e32 v52, v161
	v_mov_b32_e32 v53, v161
	v_mov_b32_e32 v54, v161
	v_mov_b32_e32 v55, v161
	v_mov_b32_e32 v56, v161
	v_mov_b32_e32 v57, v161
	s_waitcnt vmcnt(5)
	ds_write_b128 v162, v[14:17]
	ds_write_b128 v162, v[6:9] offset:9216
	ds_write_b128 v162, v[10:13] offset:18432
	s_waitcnt vmcnt(3)
	ds_write_b128 v162, v[22:25] offset:27648
	ds_write_b128 v178, v[18:21]
	s_waitcnt vmcnt(2)
	ds_write_b128 v178, v[26:29] offset:9216
	s_waitcnt vmcnt(1)
	ds_write_b128 v178, v[30:33] offset:18432
	s_waitcnt vmcnt(0)
	ds_write_b128 v178, v[34:37] offset:27648
	v_mov_b32_e32 v6, v161
	v_mov_b32_e32 v7, v161
	v_mov_b32_e32 v8, v161
	v_mov_b32_e32 v9, v161
	v_mov_b32_e32 v10, v161
	v_mov_b32_e32 v11, v161
	v_mov_b32_e32 v12, v161
	v_mov_b32_e32 v13, v161
	v_mov_b32_e32 v14, v161
	v_mov_b32_e32 v15, v161
	v_mov_b32_e32 v16, v161
	v_mov_b32_e32 v17, v161
	v_mov_b32_e32 v18, v161
	v_mov_b32_e32 v19, v161
	v_mov_b32_e32 v20, v161
	v_mov_b32_e32 v21, v161
	v_mov_b32_e32 v22, v161
	v_mov_b32_e32 v23, v161
	v_mov_b32_e32 v24, v161
	v_mov_b32_e32 v25, v161
	v_mov_b32_e32 v26, v161
	v_mov_b32_e32 v27, v161
	v_mov_b32_e32 v28, v161
	v_mov_b32_e32 v29, v161
	v_mov_b32_e32 v30, v161
	v_mov_b32_e32 v31, v161
	v_mov_b32_e32 v32, v161
	v_mov_b32_e32 v33, v161
	v_mov_b32_e32 v34, v161
	v_mov_b32_e32 v35, v161
	v_mov_b32_e32 v36, v161
	v_mov_b32_e32 v37, v161
	v_mov_b32_e32 v58, v161
	v_mov_b32_e32 v59, v161
	v_mov_b32_e32 v60, v161
	v_mov_b32_e32 v61, v161
	v_mov_b32_e32 v62, v161
	v_mov_b32_e32 v63, v161
	v_mov_b32_e32 v64, v161
	v_mov_b32_e32 v65, v161
	v_mov_b32_e32 v66, v161
	v_mov_b32_e32 v67, v161
	v_mov_b32_e32 v68, v161
	v_mov_b32_e32 v69, v161
	v_mov_b32_e32 v70, v161
	v_mov_b32_e32 v71, v161
	v_mov_b32_e32 v72, v161
	v_mov_b32_e32 v73, v161
	v_mov_b32_e32 v74, v161
	v_mov_b32_e32 v75, v161
	v_mov_b32_e32 v76, v161
	v_mov_b32_e32 v77, v161
	v_mov_b32_e32 v78, v161
	v_mov_b32_e32 v79, v161
	v_mov_b32_e32 v80, v161
	v_mov_b32_e32 v81, v161
	v_mov_b32_e32 v82, v161
	v_mov_b32_e32 v83, v161
	v_mov_b32_e32 v84, v161
	v_mov_b32_e32 v85, v161
	v_mov_b32_e32 v86, v161
	v_mov_b32_e32 v87, v161
	v_mov_b32_e32 v88, v161
	v_mov_b32_e32 v89, v161
	v_mov_b32_e32 v90, v161
	v_mov_b32_e32 v91, v161
	v_mov_b32_e32 v92, v161
	v_mov_b32_e32 v93, v161
	v_mov_b32_e32 v94, v161
	v_mov_b32_e32 v95, v161
	v_mov_b32_e32 v96, v161
	v_mov_b32_e32 v97, v161
	v_mov_b32_e32 v98, v161
	v_mov_b32_e32 v99, v161
	v_mov_b32_e32 v100, v161
	v_mov_b32_e32 v101, v161
	v_mov_b32_e32 v102, v161
	v_mov_b32_e32 v103, v161
	v_mov_b32_e32 v104, v161
	v_mov_b32_e32 v105, v161
	v_mov_b32_e32 v106, v161
	v_mov_b32_e32 v107, v161
	v_mov_b32_e32 v108, v161
	v_mov_b32_e32 v109, v161
	v_mov_b32_e32 v110, v161
	v_mov_b32_e32 v111, v161
	v_mov_b32_e32 v112, v161
	v_mov_b32_e32 v113, v161
	v_mov_b32_e32 v114, v161
	v_mov_b32_e32 v115, v161
	v_mov_b32_e32 v116, v161
	v_mov_b32_e32 v117, v161
	v_mov_b32_e32 v118, v161
	v_mov_b32_e32 v119, v161
	v_mov_b32_e32 v120, v161
	v_mov_b32_e32 v121, v161
	v_mov_b32_e32 v122, v161
	v_mov_b32_e32 v123, v161
	v_mov_b32_e32 v124, v161
	v_mov_b32_e32 v125, v161
	v_mov_b32_e32 v126, v161
	v_mov_b32_e32 v127, v161
	s_waitcnt lgkmcnt(0)
	s_barrier
	s_branch .LBB0_193

; #define GLOAD(kt) do { const int ko = (kt) * BK; \
;     ra0 = *(const uint4*)(gA + ko); ra1 = *(const uint4*)(gA + sA + ko); ra2 = *(const uint4*)(gA + 2 * sA + ko); ra3 = *(const uint4*)(gA + 3 * sA + ko); \
;     rb0 = *(const uint4*)(gB + ko); rb1 = *(const uint4*)(gB + sB + ko); rb2 = *(const uint4*)(gB + 2 * sB + ko); rb3 = *(const uint4*)(gB + 3 * sB + ko); } while (0)
; #define LSTORE(st) do { \
;     *(uint4*)(lA + (st) * ASZ) = ra0; *(uint4*)(lA + (st) * ASZ + 64 * LDT) = ra1; *(uint4*)(lA + (st) * ASZ + 128 * LDT) = ra2; *(uint4*)(lA + (st) * ASZ + 192 * LDT) = ra3; \
;     *(uint4*)(lB + (st) * BSZ) = rb0; *(uint4*)(lB + (st) * BSZ + 64 * LDT) = rb1; *(uint4*)(lB + (st) * BSZ + 128 * LDT) = rb2; *(uint4*)(lB + (st) * BSZ + 192 * LDT) = rb3; } while (0)
; template <class Epi>
; DI void gemm_tile(const GemmDesc g, int m0, int n0, unsigned char* lds, Epi& epi) {
;     ...
;   __syncthreads();
;   GLOAD(0);
;   LSTORE(0);
;   __syncthreads();
;   for (int kt = 0; kt < nk; kt += 2) {
;     const bool h1 = kt + 1 < nk, h2 = kt + 2 < nk;
;     if (h1) GLOAD(kt + 1);
;     COMPUTE(0);
;     if (h1) LSTORE(1);
;     __syncthreads();
.LBB0_193:
	v_lshl_add_u64 v[240:241], v[166:167], 0, v[160:161]
	v_lshl_add_u64 v[238:239], v[168:169], 0, v[160:161]
	v_add_co_u32_e32 v128, vcc, 0x5a68000, v240
	s_nop 1
	v_addc_co_u32_e32 v129, vcc, 0, v241, vcc
	global_load_dwordx4 v[128:131], v[128:129], off offset:128
	v_add_co_u32_e32 v132, vcc, 0x5a88000, v240
	s_nop 1
	v_addc_co_u32_e32 v133, vcc, 0, v241, vcc
	global_load_dwordx4 v[132:135], v[132:133], off offset:128
	v_add_co_u32_e32 v136, vcc, 0x5aa8000, v240
	s_nop 1
	v_addc_co_u32_e32 v137, vcc, 0, v241, vcc
	global_load_dwordx4 v[136:139], v[136:137], off offset:128
	v_add_co_u32_e32 v140, vcc, 0x5ac8000, v240
	s_nop 1
	v_addc_co_u32_e32 v141, vcc, 0, v241, vcc
	global_load_dwordx4 v[140:143], v[140:141], off offset:128
	v_add_co_u32_e32 v144, vcc, 0x10000, v238
	s_nop 1
	v_addc_co_u32_e32 v145, vcc, 0, v239, vcc
	global_load_dwordx4 v[144:147], v[144:145], off offset:128
	v_add_co_u32_e32 v148, vcc, 0x30000, v238
	s_nop 1
	v_addc_co_u32_e32 v149, vcc, 0, v239, vcc
	global_load_dwordx4 v[148:151], v[148:149], off offset:128
	v_add_co_u32_e32 v152, vcc, 0x50000, v238
	s_nop 1
	v_addc_co_u32_e32 v153, vcc, 0, v239, vcc
	global_load_dwordx4 v[152:155], v[152:153], off offset:128
	v_add_co_u32_e32 v156, vcc, 0x70000, v238
	s_nop 1
	v_addc_co_u32_e32 v157, vcc, 0, v239, vcc
	global_load_dwordx4 v[156:159], v[156:157], off offset:128
	ds_read_b128 v[200:203], v163
	ds_read_b128 v[196:199], v164
	ds_read_b128 v[214:217], v163 offset:4608
	ds_read_b128 v[230:233], v164 offset:4608
	ds_read_b128 v[234:237], v164 offset:9216
	ds_read_b128 v[244:247], v164 offset:13824
	s_waitcnt lgkmcnt(4)
	v_mfma_f32_32x32x16_bf16 v[112:127], v[196:199], v[200:203], v[112:127]
	ds_read_b128 v[210:213], v163 offset:32
	s_waitcnt lgkmcnt(4)
	v_mfma_f32_32x32x16_bf16 v[96:111], v[196:199], v[214:217], v[96:111]
	ds_read_b128 v[204:207], v164 offset:32
	s_waitcnt lgkmcnt(4)
	v_mfma_f32_32x32x16_bf16 v[80:95], v[230:233], v[200:203], v[80:95]
	ds_read_b128 v[218:221], v163 offset:4640
	v_mfma_f32_32x32x16_bf16 v[64:79], v[230:233], v[214:217], v[64:79]
	ds_read_b128 v[222:225], v164 offset:4640
	s_waitcnt lgkmcnt(5)
	v_mfma_f32_32x32x16_bf16 v[48:63], v[234:237], v[200:203], v[48:63]
	ds_read_b128 v[226:229], v164 offset:9248
	v_mfma_f32_32x32x16_bf16 v[32:47], v[234:237], v[214:217], v[32:47]
		s_cmp_lt_u32 s9, 14
		s_cselect_b64 s[6:7], -1, 0
		s_cmp_gt_u32 s9, 13
		s_cselect_b64 s[4:5], -1, 0
	ds_read_b128 v[170:173], v164 offset:13856
	s_waitcnt lgkmcnt(6)
	v_mfma_f32_32x32x16_bf16 v[16:31], v[244:247], v[200:203], v[16:31]
		v_lshl_add_u64 v[250:251], v[166:167], 0, v[160:161]
		v_lshl_add_u64 v[248:249], v[168:169], 0, v[160:161]
	v_mfma_f32_32x32x16_bf16 v[0:15], v[244:247], v[214:217], v[0:15]
	s_waitcnt lgkmcnt(4)
	v_mfma_f32_32x32x16_bf16 v[112:127], v[204:207], v[210:213], v[112:127]
	ds_read_b128 v[200:203], v163 offset:64
	s_waitcnt lgkmcnt(4)
	v_mfma_f32_32x32x16_bf16 v[96:111], v[204:207], v[218:221], v[96:111]
	ds_read_b128 v[196:199], v164 offset:64
	s_waitcnt lgkmcnt(4)
	v_mfma_f32_32x32x16_bf16 v[80:95], v[222:225], v[210:213], v[80:95]
	ds_read_b128 v[214:217], v163 offset:4672
	v_mfma_f32_32x32x16_bf16 v[64:79], v[222:225], v[218:221], v[64:79]
	ds_read_b128 v[230:233], v164 offset:4672
	s_waitcnt lgkmcnt(5)
	v_mfma_f32_32x32x16_bf16 v[48:63], v[226:229], v[210:213], v[48:63]
	ds_read_b128 v[234:237], v164 offset:9280
	v_mfma_f32_32x32x16_bf16 v[32:47], v[226:229], v[218:221], v[32:47]
	ds_read_b128 v[244:247], v164 offset:13888
	s_waitcnt lgkmcnt(6)
	v_mfma_f32_32x32x16_bf16 v[16:31], v[170:173], v[210:213], v[16:31]
	v_mfma_f32_32x32x16_bf16 v[0:15], v[170:173], v[218:221], v[0:15]
	s_waitcnt lgkmcnt(4)
	v_mfma_f32_32x32x16_bf16 v[112:127], v[196:199], v[200:203], v[112:127]
	ds_read_b128 v[210:213], v163 offset:96
	s_waitcnt lgkmcnt(4)
	v_mfma_f32_32x32x16_bf16 v[96:111], v[196:199], v[214:217], v[96:111]
	ds_read_b128 v[204:207], v164 offset:96
	s_waitcnt lgkmcnt(4)
	v_mfma_f32_32x32x16_bf16 v[80:95], v[230:233], v[200:203], v[80:95]
	ds_read_b128 v[218:221], v163 offset:4704
	v_mfma_f32_32x32x16_bf16 v[64:79], v[230:233], v[214:217], v[64:79]
	ds_read_b128 v[222:225], v164 offset:4704
	s_waitcnt lgkmcnt(5)
	v_mfma_f32_32x32x16_bf16 v[48:63], v[234:237], v[200:203], v[48:63]
	ds_read_b128 v[226:229], v164 offset:9312
	v_mfma_f32_32x32x16_bf16 v[32:47], v[234:237], v[214:217], v[32:47]
	ds_read_b128 v[170:173], v164 offset:13920
	s_waitcnt lgkmcnt(6)
	v_mfma_f32_32x32x16_bf16 v[16:31], v[244:247], v[200:203], v[16:31]
	v_mfma_f32_32x32x16_bf16 v[0:15], v[244:247], v[214:217], v[0:15]
	s_waitcnt lgkmcnt(4)
	v_mfma_f32_32x32x16_bf16 v[112:127], v[204:207], v[210:213], v[112:127]
	s_waitcnt vmcnt(7)
	ds_write_b128 v162, v[128:131] offset:36864
	s_waitcnt lgkmcnt(4)
	v_mfma_f32_32x32x16_bf16 v[96:111], v[204:207], v[218:221], v[96:111]
	s_waitcnt vmcnt(6)
	ds_write_b128 v162, v[132:135] offset:46080
	s_waitcnt lgkmcnt(4)
	v_mfma_f32_32x32x16_bf16 v[80:95], v[222:225], v[210:213], v[80:95]
	s_waitcnt vmcnt(5)
	ds_write_b128 v162, v[136:139] offset:55296
	v_mfma_f32_32x32x16_bf16 v[64:79], v[222:225], v[218:221], v[64:79]
	s_waitcnt vmcnt(4)
	ds_write_b128 v162, v[140:143] offset:64512
	s_waitcnt lgkmcnt(5)
	v_mfma_f32_32x32x16_bf16 v[48:63], v[226:229], v[210:213], v[48:63]
	s_waitcnt vmcnt(3)
	ds_write_b128 v178, v[144:147] offset:36864
	v_mfma_f32_32x32x16_bf16 v[32:47], v[226:229], v[218:221], v[32:47]
	s_waitcnt vmcnt(2)
	ds_write_b128 v178, v[148:151] offset:46080
	s_waitcnt lgkmcnt(6)
	v_mfma_f32_32x32x16_bf16 v[16:31], v[170:173], v[210:213], v[16:31]
	s_waitcnt vmcnt(1)
	ds_write_b128 v178, v[152:155] offset:55296
	v_mfma_f32_32x32x16_bf16 v[0:15], v[170:173], v[218:221], v[0:15]
	s_waitcnt vmcnt(0)
	ds_write_b128 v178, v[156:159] offset:64512
	s_and_b64 vcc, exec, s[4:5]
	s_waitcnt lgkmcnt(0)
	s_barrier
; #define GLOAD(kt) do { const int ko = (kt) * BK; \
;     ra0 = *(const uint4*)(gA + ko); ra1 = *(const uint4*)(gA + sA + ko); ra2 = *(const uint4*)(gA + 2 * sA + ko); ra3 = *(const uint4*)(gA + 3 * sA + ko); \
;     rb0 = *(const uint4*)(gB + ko); rb1 = *(const uint4*)(gB + sB + ko); rb2 = *(const uint4*)(gB + 2 * sB + ko); rb3 = *(const uint4*)(gB + 3 * sB + ko); } while (0)
; #define LSTORE(st) do { \
;     *(uint4*)(lA + (st) * ASZ) = ra0; *(uint4*)(lA + (st) * ASZ + 64 * LDT) = ra1; *(uint4*)(lA + (st) * ASZ + 128 * LDT) = ra2; *(uint4*)(lA + (st) * ASZ + 192 * LDT) = ra3; \
;     *(uint4*)(lB + (st) * BSZ) = rb0; *(uint4*)(lB + (st) * BSZ + 64 * LDT) = rb1; *(uint4*)(lB + (st) * BSZ + 128 * LDT) = rb2; *(uint4*)(lB + (st) * BSZ + 192 * LDT) = rb3; } while (0)
; template <class Epi>
; DI void gemm_tile(const GemmDesc g, int m0, int n0, unsigned char* lds, Epi& epi) {
;     ...
;   for (int kt = 0; kt < nk; kt += 2) {
;     const bool h1 = kt + 1 < nk, h2 = kt + 2 < nk;
;     if (h1) GLOAD(kt + 1);
;     COMPUTE(0);
;     if (h1) LSTORE(1);
;     __syncthreads();
;     if (h1) {
;       if (h2) GLOAD(kt + 2);
;       COMPUTE(1);
;       if (h2) LSTORE(0);
;       __syncthreads();
;     }
;   }
	s_cbranch_vccnz .LBB0_195
	v_add_co_u32_e32 v128, vcc, 0x5a68000, v250
	s_nop 1
	v_addc_co_u32_e32 v129, vcc, 0, v251, vcc
	global_load_dwordx4 v[128:131], v[128:129], off offset:256
	v_add_co_u32_e32 v132, vcc, 0x5a88000, v250
	s_nop 1
	v_addc_co_u32_e32 v133, vcc, 0, v251, vcc
	global_load_dwordx4 v[132:135], v[132:133], off offset:256
	v_add_co_u32_e32 v136, vcc, 0x5aa8000, v250
	s_nop 1
	v_addc_co_u32_e32 v137, vcc, 0, v251, vcc
	global_load_dwordx4 v[136:139], v[136:137], off offset:256
	v_add_co_u32_e32 v140, vcc, 0x5ac8000, v250
	s_nop 1
	v_addc_co_u32_e32 v141, vcc, 0, v251, vcc
	global_load_dwordx4 v[140:143], v[140:141], off offset:256
	v_add_co_u32_e32 v144, vcc, 0x10000, v248
	s_nop 1
	v_addc_co_u32_e32 v145, vcc, 0, v249, vcc
	global_load_dwordx4 v[144:147], v[144:145], off offset:256
	v_add_co_u32_e32 v148, vcc, 0x30000, v248
	s_nop 1
	v_addc_co_u32_e32 v149, vcc, 0, v249, vcc
	global_load_dwordx4 v[148:151], v[148:149], off offset:256
	v_add_co_u32_e32 v152, vcc, 0x50000, v248
	s_nop 1
	v_addc_co_u32_e32 v153, vcc, 0, v249, vcc
	global_load_dwordx4 v[152:155], v[152:153], off offset:256
	v_add_co_u32_e32 v156, vcc, 0x70000, v248
	s_nop 1
	v_addc_co_u32_e32 v157, vcc, 0, v249, vcc
	global_load_dwordx4 v[156:159], v[156:157], off offset:256
.LBB0_195:
	s_andn2_b64 vcc, exec, s[6:7]
	ds_read_b128 v[200:203], v163 offset:36864
	ds_read_b128 v[196:199], v164 offset:36864
	ds_read_b128 v[214:217], v163 offset:41472
	ds_read_b128 v[230:233], v164 offset:41472
	ds_read_b128 v[234:237], v164 offset:46080
	ds_read_b128 v[244:247], v164 offset:50688
	s_waitcnt lgkmcnt(4)
	v_mfma_f32_32x32x16_bf16 v[112:127], v[196:199], v[200:203], v[112:127]
	ds_read_b128 v[210:213], v163 offset:36896
	s_waitcnt lgkmcnt(4)
	v_mfma_f32_32x32x16_bf16 v[96:111], v[196:199], v[214:217], v[96:111]
	ds_read_b128 v[204:207], v164 offset:36896
	s_waitcnt lgkmcnt(4)
	v_mfma_f32_32x32x16_bf16 v[80:95], v[230:233], v[200:203], v[80:95]
	ds_read_b128 v[218:221], v163 offset:41504
	v_mfma_f32_32x32x16_bf16 v[64:79], v[230:233], v[214:217], v[64:79]
	ds_read_b128 v[222:225], v164 offset:41504
	s_waitcnt lgkmcnt(5)
	v_mfma_f32_32x32x16_bf16 v[48:63], v[234:237], v[200:203], v[48:63]
	ds_read_b128 v[226:229], v164 offset:46112
	v_mfma_f32_32x32x16_bf16 v[32:47], v[234:237], v[214:217], v[32:47]
	ds_read_b128 v[170:173], v164 offset:50720
	s_waitcnt lgkmcnt(6)
	v_mfma_f32_32x32x16_bf16 v[16:31], v[244:247], v[200:203], v[16:31]
	v_mfma_f32_32x32x16_bf16 v[0:15], v[244:247], v[214:217], v[0:15]
	s_waitcnt lgkmcnt(4)
	v_mfma_f32_32x32x16_bf16 v[112:127], v[204:207], v[210:213], v[112:127]
	ds_read_b128 v[200:203], v163 offset:36928
	s_waitcnt lgkmcnt(4)
	v_mfma_f32_32x32x16_bf16 v[96:111], v[204:207], v[218:221], v[96:111]
	ds_read_b128 v[196:199], v164 offset:36928
	s_waitcnt lgkmcnt(4)
	v_mfma_f32_32x32x16_bf16 v[80:95], v[222:225], v[210:213], v[80:95]
	ds_read_b128 v[214:217], v163 offset:41536
	v_mfma_f32_32x32x16_bf16 v[64:79], v[222:225], v[218:221], v[64:79]
	ds_read_b128 v[230:233], v164 offset:41536
	s_waitcnt lgkmcnt(5)
	v_mfma_f32_32x32x16_bf16 v[48:63], v[226:229], v[210:213], v[48:63]
	ds_read_b128 v[234:237], v164 offset:46144
	v_mfma_f32_32x32x16_bf16 v[32:47], v[226:229], v[218:221], v[32:47]
	ds_read_b128 v[244:247], v164 offset:50752
	s_waitcnt lgkmcnt(6)
	v_mfma_f32_32x32x16_bf16 v[16:31], v[170:173], v[210:213], v[16:31]
	v_mfma_f32_32x32x16_bf16 v[0:15], v[170:173], v[218:221], v[0:15]
	s_waitcnt lgkmcnt(4)
	v_mfma_f32_32x32x16_bf16 v[112:127], v[196:199], v[200:203], v[112:127]
	ds_read_b128 v[210:213], v163 offset:36960
	s_waitcnt lgkmcnt(4)
	v_mfma_f32_32x32x16_bf16 v[96:111], v[196:199], v[214:217], v[96:111]
	ds_read_b128 v[204:207], v164 offset:36960
	s_waitcnt lgkmcnt(4)
	v_mfma_f32_32x32x16_bf16 v[80:95], v[230:233], v[200:203], v[80:95]
	ds_read_b128 v[218:221], v163 offset:41568
	v_mfma_f32_32x32x16_bf16 v[64:79], v[230:233], v[214:217], v[64:79]
	ds_read_b128 v[222:225], v164 offset:41568
	s_waitcnt lgkmcnt(5)
	v_mfma_f32_32x32x16_bf16 v[48:63], v[234:237], v[200:203], v[48:63]
	ds_read_b128 v[226:229], v164 offset:46176
	v_mfma_f32_32x32x16_bf16 v[32:47], v[234:237], v[214:217], v[32:47]
	ds_read_b128 v[170:173], v164 offset:50784
	s_waitcnt lgkmcnt(6)
	v_mfma_f32_32x32x16_bf16 v[16:31], v[244:247], v[200:203], v[16:31]
	v_mfma_f32_32x32x16_bf16 v[0:15], v[244:247], v[214:217], v[0:15]
	s_cbranch_vccnz .Lg2_b_plain
	s_waitcnt lgkmcnt(4)
	v_mfma_f32_32x32x16_bf16 v[112:127], v[204:207], v[210:213], v[112:127]
	s_waitcnt vmcnt(7)
	ds_write_b128 v162, v[128:131]
	s_waitcnt lgkmcnt(4)
	v_mfma_f32_32x32x16_bf16 v[96:111], v[204:207], v[218:221], v[96:111]
	s_waitcnt vmcnt(6)
	ds_write_b128 v162, v[132:135] offset:9216
	s_waitcnt lgkmcnt(4)
	v_mfma_f32_32x32x16_bf16 v[80:95], v[222:225], v[210:213], v[80:95]
	s_waitcnt vmcnt(5)
	ds_write_b128 v162, v[136:139] offset:18432
	v_mfma_f32_32x32x16_bf16 v[64:79], v[222:225], v[218:221], v[64:79]
	s_waitcnt vmcnt(4)
	ds_write_b128 v162, v[140:143] offset:27648
	s_waitcnt lgkmcnt(5)
	v_mfma_f32_32x32x16_bf16 v[48:63], v[226:229], v[210:213], v[48:63]
	s_waitcnt vmcnt(3)
	ds_write_b128 v178, v[144:147]
	v_mfma_f32_32x32x16_bf16 v[32:47], v[226:229], v[218:221], v[32:47]
	s_waitcnt vmcnt(2)
	ds_write_b128 v178, v[148:151] offset:9216
	s_waitcnt lgkmcnt(6)
	v_mfma_f32_32x32x16_bf16 v[16:31], v[170:173], v[210:213], v[16:31]
	s_waitcnt vmcnt(1)
	ds_write_b128 v178, v[152:155] offset:18432
	v_mfma_f32_32x32x16_bf16 v[0:15], v[170:173], v[218:221], v[0:15]
	s_waitcnt vmcnt(0)
	ds_write_b128 v178, v[156:159] offset:27648
	s_branch .LBB0_192
.Lg2_b_plain:
	s_waitcnt lgkmcnt(4)
	v_mfma_f32_32x32x16_bf16 v[112:127], v[204:207], v[210:213], v[112:127]
	s_waitcnt lgkmcnt(3)
	v_mfma_f32_32x32x16_bf16 v[96:111], v[204:207], v[218:221], v[96:111]
	s_waitcnt lgkmcnt(2)
	v_mfma_f32_32x32x16_bf16 v[80:95], v[222:225], v[210:213], v[80:95]
	v_mfma_f32_32x32x16_bf16 v[64:79], v[222:225], v[218:221], v[64:79]
	s_waitcnt lgkmcnt(1)
	v_mfma_f32_32x32x16_bf16 v[48:63], v[226:229], v[210:213], v[48:63]
	v_mfma_f32_32x32x16_bf16 v[32:47], v[226:229], v[218:221], v[32:47]
	s_waitcnt lgkmcnt(0)
	v_mfma_f32_32x32x16_bf16 v[16:31], v[170:173], v[210:213], v[16:31]
	v_mfma_f32_32x32x16_bf16 v[0:15], v[170:173], v[218:221], v[0:15]
	s_branch .LBB0_192

; DI void phase7(const Params& P, unsigned char* lds) {
;   GemmDesc g{(const bf16_t*)(P.ws + OFF_MIX), 1024, (const bf16_t*)(P.ws + OFF_WOUT_T), 1024, 1024};
;   EpiOut e{P.x, (const float*)(P.ws + OFF_MOD), (bf16_t*)(P.ws + OFF_X1)};
;   for (int t = blockIdx.x; t < 64 * 4; t += gridDim.x) gemm_tile(g, (t >> 2) * BM, (t & 3) * BN, lds, e);
.LBB0_1379:
	s_cmp_lt_i32 s96, 8
	s_waitcnt lgkmcnt(0)
	s_cselect_b64 s[0:1], -1, 0
	s_cmp_gt_i32 s97, 7
	s_cselect_b64 s[2:3], -1, 0
	s_and_b64 s[0:1], s[0:1], s[2:3]
	s_andn2_b64 vcc, exec, s[0:1]
	s_cbranch_vccnz .LBB0_1443
	s_cmpk_gt_i32 s76, 0xff
	s_cbranch_scc1 .LBB0_1389
	s_add_u32 s4, s94, 0x5a68000
	s_addc_u32 s5, s95, 0
	s_add_u32 s6, s94, 0x710000
	s_addc_u32 s7, s95, 0
	s_add_u32 s8, s94, 0xb00000
	s_addc_u32 s9, s95, 0
	s_add_u32 s10, s78, 0xd8
	s_addc_u32 s11, s79, 0
	v_mov_b32_e32 v161, 0
	s_movk_i32 s0, 0x90
	s_mov_b32 s1, 0x12000
	s_mov_b32 s2, 0x20000
	s_mov_b32 s3, 0x40000
	s_mov_b32 s18, 0x60000
	s_mov_b32 s19, 0x5a68000
	s_mov_b32 s20, 0x5a88000
	s_mov_b32 s21, 0x5aa8000
	s_mov_b32 s22, 0x5ac8000
	s_mov_b32 s23, 0x710000
	s_mov_b32 s24, 0x730000
	s_mov_b32 s25, 0x750000
	s_mov_b32 s26, 0x770000
	s_mov_b64 s[12:13], 0x100
	s_movk_i32 s27, 0xc00
	v_mov_b32_e32 v174, 0x800
	s_and_b32 s28, s76, 7
	s_lshl_b32 s28, s28, 5
	s_lshr_b32 s14, s76, 3
	s_or_b32 s28, s28, s14
	s_branch .LBB0_1383
